# epilogue de-serialization + scan: fused single-element cvt_pk+v_perm pairs into one v_cvt_pk_bf16_f32 (116 sites)
# speedup vs baseline: 1.0141x; 1.0141x over previous
.LBB0_611:
	ds_read_b128 v[20:23], v194
	ds_read_b128 v[36:39], v194 offset:32
	ds_read_b128 v[24:27], v201
	ds_read_b128 v[40:43], v201 offset:32
	ds_read_b128 v[44:47], v194 offset:64
	ds_read_b128 v[48:51], v194 offset:96
	ds_read_b128 v[120:123], v201 offset:64
	ds_read_b128 v[210:213], v201 offset:96
	s_waitcnt lgkmcnt(5)
	v_mfma_f32_32x32x16_bf16 v[20:35], v[20:23], v[24:27], 0
	s_andn2_b64 vcc, exec, s[40:41]
	s_waitcnt lgkmcnt(4)
	v_mfma_f32_32x32x16_bf16 v[20:35], v[36:39], v[40:43], v[20:35]
	s_waitcnt lgkmcnt(1)
	v_mfma_f32_32x32x16_bf16 v[20:35], v[44:47], v[120:123], v[20:35]
	s_waitcnt lgkmcnt(0)
	v_mfma_f32_32x32x16_bf16 v[20:35], v[48:51], v[210:213], v[20:35]
	s_nop 11
	v_cndmask_b32_e64 v36, 0, v20, s[62:63]
	v_cndmask_b32_e64 v37, v21, 0, s[64:65]
	v_cndmask_b32_e64 v38, 0, v22, s[66:67]
	v_cndmask_b32_e64 v39, 0, v23, s[68:69]
	v_cndmask_b32_e64 v40, 0, v24, s[70:71]
	v_cndmask_b32_e64 v41, 0, v25, s[72:73]
	v_cndmask_b32_e64 v42, 0, v26, s[74:75]
	v_cndmask_b32_e64 v43, 0, v27, s[76:77]
	v_cndmask_b32_e64 v49, 0, v34, s[90:91]
	v_sub_f32_e32 v2, v158, v36
	v_sub_f32_e32 v1, v159, v37
	v_cndmask_b32_e64 v50, 0, v35, s[92:93]
	v_cndmask_b32_e64 v44, 0, v28, s[78:79]
	v_cndmask_b32_e64 v47, 0, v31, s[84:85]
	v_sub_f32_e32 v31, v161, v39
	v_sub_f32_e32 v28, v162, v40
	v_cvt_pk_bf16_f32 v35, v38, v39
	v_cvt_pk_bf16_f32 v34, v36, v37
	v_cndmask_b32_e64 v45, 0, v29, s[80:81]
	v_cndmask_b32_e64 v48, 0, v32, s[86:87]
	v_sub_f32_e32 v32, v160, v38
	v_add_u32_e32 v38, s3, v174
	v_cvt_pk_bf16_f32 v37, v42, v43
	v_cvt_pk_bf16_f32 v36, v40, v41
	v_cndmask_b32_e64 v46, 0, v30, s[82:83]
	v_cndmask_b32_e64 v33, 0, v33, s[88:89]
	ds_write2_b64 v38, v[34:35], v[36:37] offset1:2
	v_sub_f32_e32 v21, v171, v33
	v_cvt_pk_bf16_f32 v34, v44, v45
	v_cvt_pk_bf16_f32 v35, v46, v47
	v_cvt_pk_bf16_f32 v36, v48, v33
	v_cndmask_b32_e64 v33, 0, 1, s[40:41]
	v_sub_f32_e32 v25, v163, v41
	v_sub_f32_e32 v30, v164, v42
	v_sub_f32_e32 v29, v165, v43
	v_sub_f32_e32 v24, v166, v44
	v_sub_f32_e32 v23, v167, v45
	v_sub_f32_e32 v26, v168, v46
	v_sub_f32_e32 v27, v169, v47
	v_sub_f32_e32 v20, v170, v48
	v_sub_f32_e32 v22, v172, v49
	v_sub_f32_e32 v3, v173, v50
	v_cvt_pk_bf16_f32 v37, v49, v50
	v_cmp_ne_u32_e64 s[36:37], 1, v33
	ds_write2_b64 v38, v[34:35], v[36:37] offset0:4 offset1:6
	s_cbranch_vccnz .LBB0_613
	v_cvt_pk_bf16_f32 v33, v32, v31
	v_cvt_pk_bf16_f32 v32, v2, v1
	v_cvt_pk_bf16_f32 v29, v30, v29
	v_cvt_pk_bf16_f32 v28, v28, v25
	v_add_u32_e32 v1, 0, v174
	v_cvt_pk_bf16_f32 v25, v26, v27
	v_cvt_pk_bf16_f32 v24, v24, v23
	v_add_u32_e32 v1, 0x16800, v1
	v_cvt_pk_bf16_f32 v3, v22, v3
	v_cvt_pk_bf16_f32 v2, v20, v21
	ds_write2_b64 v1, v[32:33], v[28:29] offset1:2
	ds_write2_b64 v1, v[24:25], v[2:3] offset0:4 offset1:6
.LBB0_613:
	v_add_u32_e32 v1, v149, v175
	ds_read_b128 v[20:23], v194
	ds_read_b128 v[36:39], v194 offset:32
	ds_read_b128 v[24:27], v1
	ds_read_b128 v[40:43], v1 offset:32
	ds_read_b128 v[44:47], v194 offset:64
	ds_read_b128 v[48:51], v194 offset:96
	ds_read_b128 v[120:123], v1 offset:64
	ds_read_b128 v[210:213], v1 offset:96
	s_waitcnt lgkmcnt(5)
	v_mfma_f32_32x32x16_bf16 v[20:35], v[20:23], v[24:27], 0
	s_and_b64 vcc, exec, s[36:37]
	s_waitcnt lgkmcnt(4)
	v_mfma_f32_32x32x16_bf16 v[20:35], v[36:39], v[40:43], v[20:35]
	s_waitcnt lgkmcnt(1)
	v_mfma_f32_32x32x16_bf16 v[20:35], v[44:47], v[120:123], v[20:35]
	s_waitcnt lgkmcnt(0)
	v_mfma_f32_32x32x16_bf16 v[20:35], v[48:51], v[210:213], v[20:35]
	s_nop 11
	v_cndmask_b32_e64 v36, 0, v20, s[94:95]
	v_cndmask_b32_e64 v37, v21, 0, s[96:97]
	v_cndmask_b32_e64 v38, 0, v22, s[4:5]
	v_cndmask_b32_e64 v39, 0, v23, s[6:7]
	v_cndmask_b32_e64 v40, 0, v24, s[8:9]
	v_cndmask_b32_e64 v41, 0, v25, s[10:11]
	v_cndmask_b32_e64 v42, 0, v26, s[12:13]
	v_cndmask_b32_e64 v43, 0, v27, s[14:15]
	v_cndmask_b32_e64 v49, 0, v34, s[28:29]
	v_sub_f32_e32 v2, v176, v36
	v_sub_f32_e32 v1, v177, v37
	v_cndmask_b32_e64 v50, 0, v35, s[30:31]
	v_cndmask_b32_e64 v44, 0, v28, s[16:17]
	v_cndmask_b32_e64 v47, 0, v31, s[22:23]
	v_sub_f32_e32 v31, v179, v39
	v_sub_f32_e32 v28, v180, v40
	v_cvt_pk_bf16_f32 v35, v38, v39
	v_cvt_pk_bf16_f32 v34, v36, v37
	v_cndmask_b32_e64 v45, 0, v29, s[18:19]
	v_cndmask_b32_e64 v46, 0, v30, s[20:21]
	v_cndmask_b32_e64 v48, 0, v32, s[24:25]
	v_sub_f32_e32 v32, v178, v38
	v_add_u32_e32 v38, s3, v195
	v_cvt_pk_bf16_f32 v37, v42, v43
	v_cvt_pk_bf16_f32 v36, v40, v41
	v_cndmask_b32_e64 v33, 0, v33, s[26:27]
	ds_write2_b64 v38, v[34:35], v[36:37] offset1:2
	v_sub_f32_e32 v21, v189, v33
	v_cvt_pk_bf16_f32 v35, v46, v47
	v_cvt_pk_bf16_f32 v34, v44, v45
	v_sub_f32_e32 v25, v181, v41
	v_sub_f32_e32 v30, v182, v42
	v_sub_f32_e32 v29, v183, v43
	v_sub_f32_e32 v24, v184, v44
	v_sub_f32_e32 v23, v185, v45
	v_sub_f32_e32 v26, v186, v46
	v_sub_f32_e32 v27, v187, v47
	v_sub_f32_e32 v20, v188, v48
	v_sub_f32_e32 v22, v190, v49
	v_sub_f32_e32 v3, v191, v50
	v_cvt_pk_bf16_f32 v37, v49, v50
	v_cvt_pk_bf16_f32 v36, v48, v33
	ds_write2_b64 v38, v[34:35], v[36:37] offset0:4 offset1:6
	s_cbranch_vccnz .LBB0_615
	v_cvt_pk_bf16_f32 v33, v32, v31
	v_cvt_pk_bf16_f32 v32, v2, v1
	v_cvt_pk_bf16_f32 v29, v30, v29
	v_cvt_pk_bf16_f32 v28, v28, v25
	v_add_u32_e32 v1, 0, v195
	v_cvt_pk_bf16_f32 v25, v26, v27
	v_cvt_pk_bf16_f32 v24, v24, v23
	v_add_u32_e32 v1, 0x16800, v1
	v_cvt_pk_bf16_f32 v3, v22, v3
	v_cvt_pk_bf16_f32 v2, v20, v21
	ds_write2_b64 v1, v[32:33], v[28:29] offset1:2
	ds_write2_b64 v1, v[24:25], v[2:3] offset0:4 offset1:6

.LBB0_619:
	s_nop 11
	v_add_u32_e32 v36, s36, v205
	v_cvt_pk_bf16_f32 v3, v22, v23
	v_cvt_pk_bf16_f32 v2, v20, v21
	v_cvt_pk_bf16_f32 v21, v26, v27
	v_cvt_pk_bf16_f32 v20, v24, v25
	ds_write2_b64 v36, v[2:3], v[20:21] offset1:2
	v_cvt_pk_bf16_f32 v3, v30, v31
	v_cvt_pk_bf16_f32 v2, v28, v29
	v_cvt_pk_bf16_f32 v21, v34, v35
	v_cvt_pk_bf16_f32 v20, v32, v33
	s_mov_b64 s[36:37], -1
	s_and_b64 vcc, exec, s[0:1]
	ds_write2_b64 v36, v[2:3], v[20:21] offset0:4 offset1:6
	s_waitcnt lgkmcnt(0)
	s_barrier
	s_cbranch_vccz .LBB0_621
	s_add_i32 s36, 0, 0x16800
	v_add_u32_e32 v2, s36, v205
	ds_read2_b64 v[24:27], v2 offset1:2
	ds_read2_b64 v[32:35], v2 offset0:4 offset1:6
	v_add_u32_e32 v2, s36, v209
	v_add_u32_e32 v3, 0x14400, v1
	ds_read_b64_tr_b16 v[36:37], v2
	ds_read_b64_tr_b16 v[38:39], v2 offset:576
	ds_read_b128 v[40:43], v3
	ds_read_b64_tr_b16 v[44:45], v2 offset:2304
	ds_read_b64_tr_b16 v[46:47], v2 offset:2880
	v_add_u32_e32 v3, 0x14420, v1
	ds_read_b128 v[48:51], v3
	ds_read_b64_tr_b16 v[120:121], v2 offset:4608
	ds_read_b64_tr_b16 v[122:123], v2 offset:5184
	v_add_u32_e32 v3, 0x14440, v1
	ds_read_b128 v[210:213], v3
	ds_read_b64_tr_b16 v[226:227], v2 offset:6912
	ds_read_b64_tr_b16 v[228:229], v2 offset:7488
	v_add_u32_e32 v2, 0x14460, v1
	ds_read_b128 v[230:233], v2
	s_waitcnt lgkmcnt(13)
	v_lshlrev_b32_e32 v20, 16, v24
	v_and_b32_e32 v21, 0xffff0000, v24
	v_lshlrev_b32_e32 v22, 16, v25
	v_and_b32_e32 v23, 0xffff0000, v25
	v_lshlrev_b32_e32 v24, 16, v26
	v_and_b32_e32 v25, 0xffff0000, v26
	v_lshlrev_b32_e32 v26, 16, v27
	v_and_b32_e32 v27, 0xffff0000, v27
	s_waitcnt lgkmcnt(12)
	v_lshlrev_b32_e32 v28, 16, v32
	v_and_b32_e32 v29, 0xffff0000, v32
	v_lshlrev_b32_e32 v30, 16, v33
	v_and_b32_e32 v31, 0xffff0000, v33
	v_lshlrev_b32_e32 v32, 16, v34
	v_and_b32_e32 v33, 0xffff0000, v34
	v_lshlrev_b32_e32 v34, 16, v35
	v_and_b32_e32 v35, 0xffff0000, v35
	s_waitcnt lgkmcnt(9)
	s_nop 0
	v_mfma_f32_32x32x16_bf16 v[20:35], v[36:39], v[40:43], v[20:35]
	s_mov_b64 s[36:37], 0
	s_waitcnt lgkmcnt(6)
	v_mfma_f32_32x32x16_bf16 v[20:35], v[44:47], v[48:51], v[20:35]
	s_waitcnt lgkmcnt(3)
	v_mfma_f32_32x32x16_bf16 v[20:35], v[120:123], v[210:213], v[20:35]
	s_waitcnt lgkmcnt(0)
	v_mfma_f32_32x32x16_bf16 v[20:35], v[226:229], v[230:233], v[20:35]

.LBB0_624:
	v_add_u32_e32 v120, 0, v205
	s_nop 9
	v_add_u32_e32 v36, s39, v120
	v_cvt_pk_bf16_f32 v3, v22, v23
	v_cvt_pk_bf16_f32 v2, v20, v21
	ds_write_b64 v36, v[2:3]
	v_cvt_pk_bf16_f32 v3, v26, v27
	v_cvt_pk_bf16_f32 v2, v24, v25
	v_add_u32_e32 v20, s38, v120
	ds_write_b64 v20, v[2:3]
	v_cvt_pk_bf16_f32 v3, v30, v31
	v_cvt_pk_bf16_f32 v2, v28, v29
	v_add_u32_e32 v24, s37, v120
	ds_write_b64 v24, v[2:3]
	v_cvt_pk_bf16_f32 v3, v34, v35
	v_cvt_pk_bf16_f32 v2, v32, v33
	v_add_u32_e32 v20, s36, v120
	ds_write_b64 v20, v[2:3]
	v_cndmask_b32_e64 v2, 0, 1, s[0:1]
	v_cmp_ne_u32_e64 s[36:37], 1, v2
	s_andn2_b64 vcc, exec, s[0:1]
	s_mov_b64 s[38:39], -1
	s_waitcnt lgkmcnt(0)
	s_barrier
	s_cbranch_vccnz .LBB0_626
	v_readlane_b32 s38, v255, 1
	s_nop 1
	v_add_u32_e32 v2, s38, v205
	ds_read2_b64 v[24:27], v2 offset1:2
	ds_read2_b64 v[32:35], v2 offset0:4 offset1:6
	v_add_u32_e32 v2, s38, v209
	ds_read_b64_tr_b16 v[36:37], v2
	ds_read_b64_tr_b16 v[38:39], v2 offset:576
	ds_read_b64_tr_b16 v[40:41], v2 offset:2304
	ds_read_b64_tr_b16 v[42:43], v2 offset:2880
	ds_read_b128 v[44:47], v1 offset:46080
	ds_read_b128 v[48:51], v1 offset:46112
	ds_read_b64_tr_b16 v[122:123], v2 offset:4608
	ds_read_b64_tr_b16 v[124:125], v2 offset:5184
	ds_read_b128 v[210:213], v1 offset:46144
	ds_read_b64_tr_b16 v[226:227], v2 offset:6912
	ds_read_b64_tr_b16 v[228:229], v2 offset:7488
	ds_read_b128 v[230:233], v1 offset:46176
	s_waitcnt lgkmcnt(13)
	v_lshlrev_b32_e32 v20, 16, v24
	v_and_b32_e32 v21, 0xffff0000, v24
	v_lshlrev_b32_e32 v22, 16, v25
	v_and_b32_e32 v23, 0xffff0000, v25
	v_lshlrev_b32_e32 v24, 16, v26
	v_and_b32_e32 v25, 0xffff0000, v26
	v_lshlrev_b32_e32 v26, 16, v27
	v_and_b32_e32 v27, 0xffff0000, v27
	s_waitcnt lgkmcnt(12)
	v_lshlrev_b32_e32 v28, 16, v32
	v_and_b32_e32 v29, 0xffff0000, v32
	v_lshlrev_b32_e32 v30, 16, v33
	v_and_b32_e32 v31, 0xffff0000, v33
	v_lshlrev_b32_e32 v32, 16, v34
	v_and_b32_e32 v33, 0xffff0000, v34
	v_lshlrev_b32_e32 v34, 16, v35
	v_and_b32_e32 v35, 0xffff0000, v35
	s_waitcnt lgkmcnt(7)
	s_nop 0
	v_mfma_f32_32x32x16_bf16 v[20:35], v[36:39], v[44:47], v[20:35]
	s_mov_b64 s[38:39], 0
	s_waitcnt lgkmcnt(6)
	v_mfma_f32_32x32x16_bf16 v[20:35], v[40:43], v[48:51], v[20:35]
	s_waitcnt lgkmcnt(3)
	v_mfma_f32_32x32x16_bf16 v[20:35], v[122:125], v[210:213], v[20:35]
	s_waitcnt lgkmcnt(0)
	v_mfma_f32_32x32x16_bf16 v[20:35], v[226:229], v[230:233], v[20:35]

.LBB0_629:
	s_nop 10
	v_add_u32_e32 v36, s43, v120
	v_cvt_pk_bf16_f32 v3, v22, v23
	v_cvt_pk_bf16_f32 v2, v20, v21
	ds_write_b64 v36, v[2:3]
	v_cvt_pk_bf16_f32 v3, v26, v27
	v_cvt_pk_bf16_f32 v2, v24, v25
	v_add_u32_e32 v20, s42, v120
	ds_write_b64 v20, v[2:3]
	v_cvt_pk_bf16_f32 v3, v30, v31
	v_cvt_pk_bf16_f32 v2, v28, v29
	v_add_u32_e32 v24, s39, v120
	ds_write_b64 v24, v[2:3]
	v_cvt_pk_bf16_f32 v3, v34, v35
	v_cvt_pk_bf16_f32 v2, v32, v33
	v_add_u32_e32 v20, s38, v120
	s_and_b64 vcc, exec, s[36:37]
	s_mov_b64 s[38:39], -1
	ds_write_b64 v20, v[2:3]
	s_waitcnt lgkmcnt(0)
	s_barrier
	s_cbranch_vccnz .LBB0_631
	s_add_i32 s38, 0, 0x16800
	v_add_u32_e32 v2, s38, v205
	ds_read2_b64 v[24:27], v2 offset1:2
	ds_read2_b64 v[32:35], v2 offset0:4 offset1:6
	v_add_u32_e32 v2, s38, v209
	v_add_u32_e32 v3, 0x14400, v1
	ds_read_b64_tr_b16 v[36:37], v2
	ds_read_b64_tr_b16 v[38:39], v2 offset:576
	ds_read_b128 v[40:43], v3
	ds_read_b64_tr_b16 v[44:45], v2 offset:2304
	ds_read_b64_tr_b16 v[46:47], v2 offset:2880
	v_add_u32_e32 v3, 0x14420, v1
	ds_read_b128 v[48:51], v3
	ds_read_b64_tr_b16 v[122:123], v2 offset:4608
	ds_read_b64_tr_b16 v[124:125], v2 offset:5184
	v_add_u32_e32 v3, 0x14440, v1
	ds_read_b128 v[210:213], v3
	ds_read_b64_tr_b16 v[226:227], v2 offset:6912
	ds_read_b64_tr_b16 v[228:229], v2 offset:7488
	v_add_u32_e32 v2, 0x14460, v1
	ds_read_b128 v[230:233], v2
	s_waitcnt lgkmcnt(13)
	v_lshlrev_b32_e32 v20, 16, v24
	v_and_b32_e32 v21, 0xffff0000, v24
	v_lshlrev_b32_e32 v22, 16, v25
	v_and_b32_e32 v23, 0xffff0000, v25
	v_lshlrev_b32_e32 v24, 16, v26
	v_and_b32_e32 v25, 0xffff0000, v26
	v_lshlrev_b32_e32 v26, 16, v27
	v_and_b32_e32 v27, 0xffff0000, v27
	s_waitcnt lgkmcnt(12)
	v_lshlrev_b32_e32 v28, 16, v32
	v_and_b32_e32 v29, 0xffff0000, v32
	v_lshlrev_b32_e32 v30, 16, v33
	v_and_b32_e32 v31, 0xffff0000, v33
	v_lshlrev_b32_e32 v32, 16, v34
	v_and_b32_e32 v33, 0xffff0000, v34
	v_lshlrev_b32_e32 v34, 16, v35
	v_and_b32_e32 v35, 0xffff0000, v35
	s_waitcnt lgkmcnt(9)
	s_nop 0
	v_mfma_f32_32x32x16_bf16 v[20:35], v[36:39], v[40:43], v[20:35]
	s_mov_b64 s[38:39], 0
	s_waitcnt lgkmcnt(6)
	v_mfma_f32_32x32x16_bf16 v[20:35], v[44:47], v[48:51], v[20:35]
	s_waitcnt lgkmcnt(3)
	v_mfma_f32_32x32x16_bf16 v[20:35], v[122:125], v[210:213], v[20:35]
	s_waitcnt lgkmcnt(0)
	v_mfma_f32_32x32x16_bf16 v[20:35], v[226:229], v[230:233], v[20:35]

.LBB0_634:
	s_nop 10
	v_add_u32_e32 v36, s43, v120
	v_cvt_pk_bf16_f32 v3, v22, v23
	v_cvt_pk_bf16_f32 v2, v20, v21
	ds_write_b64 v36, v[2:3]
	v_cvt_pk_bf16_f32 v3, v26, v27
	v_cvt_pk_bf16_f32 v2, v24, v25
	v_add_u32_e32 v20, s42, v120
	ds_write_b64 v20, v[2:3]
	v_cvt_pk_bf16_f32 v3, v30, v31
	v_cvt_pk_bf16_f32 v2, v28, v29
	v_add_u32_e32 v24, s39, v120
	ds_write_b64 v24, v[2:3]
	v_cvt_pk_bf16_f32 v3, v34, v35
	v_cvt_pk_bf16_f32 v2, v32, v33
	v_add_u32_e32 v20, s38, v120
	s_and_b64 vcc, exec, s[36:37]
	s_mov_b64 s[38:39], -1
	ds_write_b64 v20, v[2:3]
	s_waitcnt lgkmcnt(0)
	s_barrier
	s_cbranch_vccnz .LBB0_636
	v_readlane_b32 s38, v255, 1
	s_nop 1
	v_add_u32_e32 v2, s38, v205
	ds_read2_b64 v[24:27], v2 offset1:2
	ds_read2_b64 v[32:35], v2 offset0:4 offset1:6
	v_add_u32_e32 v2, s38, v209
	ds_read_b64_tr_b16 v[36:37], v2
	ds_read_b64_tr_b16 v[38:39], v2 offset:576
	ds_read_b64_tr_b16 v[40:41], v2 offset:2304
	ds_read_b64_tr_b16 v[42:43], v2 offset:2880
	ds_read_b128 v[44:47], v1 offset:46080
	ds_read_b128 v[48:51], v1 offset:46112
	ds_read_b64_tr_b16 v[122:123], v2 offset:4608
	ds_read_b64_tr_b16 v[124:125], v2 offset:5184
	ds_read_b128 v[210:213], v1 offset:46144
	ds_read_b64_tr_b16 v[226:227], v2 offset:6912
	ds_read_b64_tr_b16 v[228:229], v2 offset:7488
	ds_read_b128 v[230:233], v1 offset:46176
	s_waitcnt lgkmcnt(13)
	v_lshlrev_b32_e32 v20, 16, v24
	v_and_b32_e32 v21, 0xffff0000, v24
	v_lshlrev_b32_e32 v22, 16, v25
	v_and_b32_e32 v23, 0xffff0000, v25
	v_lshlrev_b32_e32 v24, 16, v26
	v_and_b32_e32 v25, 0xffff0000, v26
	v_lshlrev_b32_e32 v26, 16, v27
	v_and_b32_e32 v27, 0xffff0000, v27
	s_waitcnt lgkmcnt(12)
	v_lshlrev_b32_e32 v28, 16, v32
	v_and_b32_e32 v29, 0xffff0000, v32
	v_lshlrev_b32_e32 v30, 16, v33
	v_and_b32_e32 v31, 0xffff0000, v33
	v_lshlrev_b32_e32 v32, 16, v34
	v_and_b32_e32 v33, 0xffff0000, v34
	v_lshlrev_b32_e32 v34, 16, v35
	v_and_b32_e32 v35, 0xffff0000, v35
	s_waitcnt lgkmcnt(7)
	s_nop 0
	v_mfma_f32_32x32x16_bf16 v[20:35], v[36:39], v[44:47], v[20:35]
	s_mov_b64 s[38:39], 0
	s_waitcnt lgkmcnt(6)
	v_mfma_f32_32x32x16_bf16 v[20:35], v[40:43], v[48:51], v[20:35]
	s_waitcnt lgkmcnt(3)
	v_mfma_f32_32x32x16_bf16 v[20:35], v[122:125], v[210:213], v[20:35]
	s_waitcnt lgkmcnt(0)
	v_mfma_f32_32x32x16_bf16 v[20:35], v[226:229], v[230:233], v[20:35]

.LBB0_639:
	s_nop 10
	v_add_u32_e32 v36, s43, v120
	v_cvt_pk_bf16_f32 v3, v22, v23
	v_cvt_pk_bf16_f32 v2, v20, v21
	ds_write_b64 v36, v[2:3]
	v_cvt_pk_bf16_f32 v3, v26, v27
	v_cvt_pk_bf16_f32 v2, v24, v25
	v_add_u32_e32 v20, s42, v120
	ds_write_b64 v20, v[2:3]
	v_cvt_pk_bf16_f32 v3, v30, v31
	v_cvt_pk_bf16_f32 v2, v28, v29
	v_add_u32_e32 v24, s39, v120
	ds_write_b64 v24, v[2:3]
	v_cvt_pk_bf16_f32 v3, v34, v35
	v_cvt_pk_bf16_f32 v2, v32, v33
	v_add_u32_e32 v20, s38, v120
	s_and_b64 vcc, exec, s[36:37]
	ds_write_b64 v20, v[2:3]
	s_waitcnt lgkmcnt(0)
	s_barrier
	s_cbranch_vccnz .LBB0_641
	s_add_i32 s38, 0, 0x16800
	v_add_u32_e32 v2, s38, v205
	ds_read2_b64 v[24:27], v2 offset1:2
	ds_read2_b64 v[32:35], v2 offset0:4 offset1:6
	v_add_u32_e32 v2, s38, v209
	v_add_u32_e32 v3, 0x14400, v1
	ds_read_b64_tr_b16 v[36:37], v2
	ds_read_b64_tr_b16 v[38:39], v2 offset:576
	ds_read_b128 v[40:43], v3
	ds_read_b64_tr_b16 v[44:45], v2 offset:2304
	ds_read_b64_tr_b16 v[46:47], v2 offset:2880
	v_add_u32_e32 v3, 0x14420, v1
	ds_read_b128 v[48:51], v3
	ds_read_b64_tr_b16 v[122:123], v2 offset:4608
	ds_read_b64_tr_b16 v[124:125], v2 offset:5184
	v_add_u32_e32 v3, 0x14440, v1
	ds_read_b128 v[210:213], v3
	ds_read_b64_tr_b16 v[226:227], v2 offset:6912
	ds_read_b64_tr_b16 v[228:229], v2 offset:7488
	v_add_u32_e32 v2, 0x14460, v1
	ds_read_b128 v[230:233], v2
	s_waitcnt lgkmcnt(13)
	v_lshlrev_b32_e32 v20, 16, v24
	v_and_b32_e32 v21, 0xffff0000, v24
	v_lshlrev_b32_e32 v22, 16, v25
	v_and_b32_e32 v23, 0xffff0000, v25
	v_lshlrev_b32_e32 v24, 16, v26
	v_and_b32_e32 v25, 0xffff0000, v26
	v_lshlrev_b32_e32 v26, 16, v27
	v_and_b32_e32 v27, 0xffff0000, v27
	s_waitcnt lgkmcnt(12)
	v_lshlrev_b32_e32 v28, 16, v32
	v_and_b32_e32 v29, 0xffff0000, v32
	v_lshlrev_b32_e32 v30, 16, v33
	v_and_b32_e32 v31, 0xffff0000, v33
	v_lshlrev_b32_e32 v32, 16, v34
	v_and_b32_e32 v33, 0xffff0000, v34
	v_lshlrev_b32_e32 v34, 16, v35
	v_and_b32_e32 v35, 0xffff0000, v35
	s_waitcnt lgkmcnt(9)
	s_nop 0
	v_mfma_f32_32x32x16_bf16 v[20:35], v[36:39], v[40:43], v[20:35]
	v_add_u32_e32 v36, 0x18c00, v120
	v_add_u32_e32 v37, 0x18c10, v120
	v_add_u32_e32 v38, 0x18c20, v120
	v_add_u32_e32 v39, 0x18c30, v120
	s_waitcnt lgkmcnt(6)
	v_mfma_f32_32x32x16_bf16 v[20:35], v[44:47], v[48:51], v[20:35]
	s_waitcnt lgkmcnt(3)
	v_mfma_f32_32x32x16_bf16 v[20:35], v[122:125], v[210:213], v[20:35]
	s_waitcnt lgkmcnt(0)
	v_mfma_f32_32x32x16_bf16 v[20:35], v[226:229], v[230:233], v[20:35]
	s_nop 11
	v_cvt_pk_bf16_f32 v2, v20, s0
	v_cvt_pk_bf16_f32 v20, v21, s0
	v_cvt_pk_bf16_f32 v3, v22, s0
	v_cvt_pk_bf16_f32 v21, v23, s0
	v_perm_b32 v3, v21, v3, s33
	v_perm_b32 v2, v20, v2, s33
	v_cvt_pk_bf16_f32 v21, v26, v27
	v_cvt_pk_bf16_f32 v20, v24, v25
	v_cvt_pk_bf16_f32 v23, v30, v31
	v_cvt_pk_bf16_f32 v22, v28, v29
	v_cvt_pk_bf16_f32 v25, v34, v35
	v_cvt_pk_bf16_f32 v24, v32, v33
	ds_write_b64 v36, v[2:3]
	ds_write_b64 v37, v[20:21]
	ds_write_b64 v38, v[22:23]
	ds_write_b64 v39, v[24:25]

.LBB0_646:
	s_nop 10
	v_add_u32_e32 v36, s38, v205
	v_cvt_pk_bf16_f32 v3, v22, v23
	v_cvt_pk_bf16_f32 v2, v20, v21
	v_cvt_pk_bf16_f32 v21, v26, v27
	v_cvt_pk_bf16_f32 v20, v24, v25
	ds_write2_b64 v36, v[2:3], v[20:21] offset1:2
	v_cvt_pk_bf16_f32 v3, v30, v31
	v_cvt_pk_bf16_f32 v2, v28, v29
	v_cvt_pk_bf16_f32 v21, v34, v35
	v_cvt_pk_bf16_f32 v20, v32, v33
	s_mov_b64 s[38:39], -1
	s_and_b64 vcc, exec, s[0:1]
	ds_write2_b64 v36, v[2:3], v[20:21] offset0:4 offset1:6
	s_waitcnt lgkmcnt(0)
	s_barrier
	s_cbranch_vccz .LBB0_650
	v_add_u32_e32 v2, 0, v209
	v_add_u32_e32 v3, 0, v208
	v_add_u32_e32 v28, 0x12000, v3
	ds_read_b64_tr_b16 v[20:21], v2 offset:36864
	ds_read_b64_tr_b16 v[22:23], v2 offset:37440
	ds_read_b64_tr_b16 v[36:37], v2 offset:39168
	ds_read_b64_tr_b16 v[38:39], v2 offset:39744
	ds_read_b64_tr_b16 v[24:25], v28
	ds_read_b64_tr_b16 v[26:27], v28 offset:576
	ds_read_b64_tr_b16 v[40:41], v28 offset:2304
	ds_read_b64_tr_b16 v[42:43], v28 offset:2880
	ds_read_b64_tr_b16 v[44:45], v2 offset:41472
	ds_read_b64_tr_b16 v[46:47], v2 offset:42048
	ds_read_b64_tr_b16 v[48:49], v2 offset:43776
	ds_read_b64_tr_b16 v[50:51], v2 offset:44352
	ds_read_b64_tr_b16 v[122:123], v28 offset:4608
	ds_read_b64_tr_b16 v[124:125], v28 offset:5184
	ds_read_b64_tr_b16 v[210:211], v28 offset:6912
	ds_read_b64_tr_b16 v[212:213], v28 offset:7488
	s_waitcnt lgkmcnt(10)
	v_mfma_f32_32x32x16_bf16 v[20:35], v[20:23], v[24:27], 0
	v_add_u32_e32 v2, 0, v207
	s_waitcnt lgkmcnt(8)
	v_mfma_f32_32x32x16_bf16 v[20:35], v[36:39], v[40:43], v[20:35]
	s_waitcnt lgkmcnt(2)
	v_mfma_f32_32x32x16_bf16 v[20:35], v[44:47], v[122:125], v[20:35]
	v_add_u32_e32 v44, 0xfc00, v3
	s_waitcnt lgkmcnt(0)
	v_mfma_f32_32x32x16_bf16 v[20:35], v[48:51], v[210:213], v[20:35]
	ds_read_b64_tr_b16 v[36:37], v3 offset:64512
	ds_read_b64_tr_b16 v[38:39], v3 offset:65088
	ds_read_b128 v[40:43], v2 offset:46080
	ds_read_b128 v[122:125], v2 offset:46112
	ds_read_b64_tr_b16 v[210:211], v44 offset:2304
	ds_read_b64_tr_b16 v[212:213], v44 offset:2880
	ds_read_b128 v[226:229], v2 offset:46144
	ds_read_b64_tr_b16 v[230:231], v44 offset:4608
	ds_read_b64_tr_b16 v[232:233], v44 offset:5184
	ds_read_b128 v[234:237], v2 offset:46176
	ds_read_b64_tr_b16 v[238:239], v44 offset:6912
	ds_read_b64_tr_b16 v[240:241], v44 offset:7488
	s_waitcnt lgkmcnt(9)
	v_mfma_f32_32x32x16_bf16 v[36:51], v[40:43], v[36:39], 0
	s_waitcnt lgkmcnt(6)
	v_mfma_f32_32x32x16_bf16 v[36:51], v[122:125], v[210:213], v[36:51]
	s_waitcnt lgkmcnt(3)
	v_mfma_f32_32x32x16_bf16 v[36:51], v[226:229], v[230:233], v[36:51]
	s_waitcnt lgkmcnt(0)
	v_mfma_f32_32x32x16_bf16 v[36:51], v[234:237], v[238:241], v[36:51]
	s_nop 11
	v_sub_f32_e32 v35, v35, v51
	v_sub_f32_e32 v34, v34, v50
	v_sub_f32_e32 v33, v33, v49
	v_sub_f32_e32 v32, v32, v48
	v_sub_f32_e32 v31, v31, v47
	v_sub_f32_e32 v30, v30, v46
	v_sub_f32_e32 v29, v29, v45
	v_sub_f32_e32 v28, v28, v44
	v_sub_f32_e32 v27, v27, v43
	v_sub_f32_e32 v26, v26, v42
	v_sub_f32_e32 v25, v25, v41
	v_sub_f32_e32 v24, v24, v40
	v_sub_f32_e32 v23, v23, v39
	v_sub_f32_e32 v22, v22, v38
	v_sub_f32_e32 v21, v21, v37
	v_sub_f32_e32 v20, v20, v36
	s_cbranch_execz .LBB0_651

.LBB0_649:
	v_add_u32_e32 v2, 0, v207
	v_add_u32_e32 v10, 0x14400, v2
	v_add_u32_e32 v11, 0, v208
	ds_read_b128 v[2:5], v10
	ds_read_b128 v[36:39], v10 offset:32
	ds_read_b64_tr_b16 v[6:7], v11 offset:18432
	ds_read_b64_tr_b16 v[8:9], v11 offset:19008
	ds_read_b64_tr_b16 v[40:41], v11 offset:20736
	ds_read_b64_tr_b16 v[42:43], v11 offset:21312
	ds_read_b128 v[44:47], v10 offset:64
	ds_read_b128 v[48:51], v10 offset:96
	ds_read_b64_tr_b16 v[122:123], v11 offset:23040
	ds_read_b64_tr_b16 v[124:125], v11 offset:23616
	ds_read_b64_tr_b16 v[210:211], v11 offset:25344
	ds_read_b64_tr_b16 v[212:213], v11 offset:25920
	s_waitcnt lgkmcnt(8)
	v_mfma_f32_32x32x16_bf16 v[2:17], v[2:5], v[6:9], 0
	ds_read_b32 v18, v150
	v_add_u32_e32 v19, 0x16800, v120
	s_waitcnt lgkmcnt(7)
	v_mfma_f32_32x32x16_bf16 v[2:17], v[36:39], v[40:43], v[2:17]
	s_waitcnt lgkmcnt(3)
	v_mfma_f32_32x32x16_bf16 v[2:17], v[44:47], v[122:125], v[2:17]
	s_waitcnt lgkmcnt(1)
	v_mfma_f32_32x32x16_bf16 v[2:17], v[48:51], v[210:213], v[2:17]
	s_nop 11
	v_pk_add_f32 v[2:3], v[98:99], v[2:3] neg_lo:[0,1] neg_hi:[0,1]
	v_pk_add_f32 v[4:5], v[100:101], v[4:5] neg_lo:[0,1] neg_hi:[0,1]
	v_pk_add_f32 v[6:7], v[102:103], v[6:7] neg_lo:[0,1] neg_hi:[0,1]
	v_pk_add_f32 v[8:9], v[104:105], v[8:9] neg_lo:[0,1] neg_hi:[0,1]
	v_pk_add_f32 v[10:11], v[106:107], v[10:11] neg_lo:[0,1] neg_hi:[0,1]
	v_pk_add_f32 v[12:13], v[108:109], v[12:13] neg_lo:[0,1] neg_hi:[0,1]
	v_pk_add_f32 v[14:15], v[110:111], v[14:15] neg_lo:[0,1] neg_hi:[0,1]
	v_pk_add_f32 v[16:17], v[112:113], v[16:17] neg_lo:[0,1] neg_hi:[0,1]
	s_waitcnt lgkmcnt(0)
	v_pk_mul_f32 v[2:3], v[18:19], v[2:3] op_sel_hi:[0,1]
	v_pk_mul_f32 v[4:5], v[18:19], v[4:5] op_sel_hi:[0,1]
	v_pk_mul_f32 v[6:7], v[18:19], v[6:7] op_sel_hi:[0,1]
	v_pk_mul_f32 v[8:9], v[18:19], v[8:9] op_sel_hi:[0,1]
	v_pk_mul_f32 v[10:11], v[18:19], v[10:11] op_sel_hi:[0,1]
	v_pk_mul_f32 v[12:13], v[18:19], v[12:13] op_sel_hi:[0,1]
	v_pk_mul_f32 v[14:15], v[18:19], v[14:15] op_sel_hi:[0,1]
	v_pk_mul_f32 v[16:17], v[18:19], v[16:17] op_sel_hi:[0,1]
	v_cvt_pk_bf16_f32 v2, v2, s0
	v_cvt_pk_bf16_f32 v18, v3, s0
	v_cvt_pk_bf16_f32 v3, v4, v5
	v_perm_b32 v2, v18, v2, s33
	v_cvt_pk_bf16_f32 v5, v8, v9
	v_cvt_pk_bf16_f32 v4, v6, v7
	ds_write2_b64 v19, v[2:3], v[4:5] offset1:2
	v_cvt_pk_bf16_f32 v3, v12, v13
	v_cvt_pk_bf16_f32 v2, v10, v11
	v_cvt_pk_bf16_f32 v5, v16, v17
	v_cvt_pk_bf16_f32 v4, v14, v15
	ds_write2_b64 v19, v[2:3], v[4:5] offset0:4 offset1:6
	s_cbranch_execz .LBB0_653
	s_branch .LBB0_654

.LBB0_651:
	v_add_u32_e32 v2, 0, v207
	v_add_u32_e32 v2, 0x14400, v2
	v_add_u32_e32 v3, 0, v208
	v_add_u32_e32 v28, 0xfc00, v3
	ds_read_b128 v[20:23], v2
	ds_read_b128 v[36:39], v2 offset:32
	ds_read_b64_tr_b16 v[24:25], v3 offset:64512
	ds_read_b64_tr_b16 v[26:27], v3 offset:65088
	ds_read_b64_tr_b16 v[40:41], v28 offset:2304
	ds_read_b64_tr_b16 v[42:43], v28 offset:2880
	ds_read_b128 v[44:47], v2 offset:64
	ds_read_b128 v[48:51], v2 offset:96
	ds_read_b64_tr_b16 v[122:123], v28 offset:4608
	ds_read_b64_tr_b16 v[124:125], v28 offset:5184
	ds_read_b64_tr_b16 v[210:211], v28 offset:6912
	ds_read_b64_tr_b16 v[212:213], v28 offset:7488
	s_waitcnt lgkmcnt(8)
	v_mfma_f32_32x32x16_bf16 v[20:35], v[20:23], v[24:27], 0
	v_add_u32_e32 v2, 0x2000, v120
	s_waitcnt lgkmcnt(6)
	v_mfma_f32_32x32x16_bf16 v[20:35], v[36:39], v[40:43], v[20:35]
	ds_read2_b64 v[36:39], v2 offset0:128 offset1:130
	ds_read2_b64 v[40:43], v2 offset0:132 offset1:134
	s_waitcnt lgkmcnt(1)
	v_lshlrev_b32_e32 v2, 16, v36
	v_and_b32_e32 v3, 0xffff0000, v36
	v_lshlrev_b32_e32 v36, 16, v37
	v_mfma_f32_32x32x16_bf16 v[20:35], v[44:47], v[122:125], v[20:35]
	v_and_b32_e32 v37, 0xffff0000, v37
	v_lshlrev_b32_e32 v44, 16, v38
	v_and_b32_e32 v38, 0xffff0000, v38
	v_lshlrev_b32_e32 v45, 16, v39
	v_and_b32_e32 v39, 0xffff0000, v39
	s_waitcnt lgkmcnt(0)
	v_lshlrev_b32_e32 v46, 16, v40
	v_and_b32_e32 v40, 0xffff0000, v40
	v_mfma_f32_32x32x16_bf16 v[20:35], v[48:51], v[210:213], v[20:35]
	v_lshlrev_b32_e32 v47, 16, v41
	v_and_b32_e32 v41, 0xffff0000, v41
	v_lshlrev_b32_e32 v48, 16, v42
	v_and_b32_e32 v42, 0xffff0000, v42
	v_lshlrev_b32_e32 v49, 16, v43
	v_and_b32_e32 v43, 0xffff0000, v43
	s_nop 5
	v_sub_f32_e32 v23, v37, v23
	v_sub_f32_e32 v22, v36, v22
	v_sub_f32_e32 v3, v3, v21
	v_sub_f32_e32 v2, v2, v20
	v_sub_f32_e32 v20, v39, v27
	v_sub_f32_e32 v21, v45, v26
	v_sub_f32_e32 v25, v38, v25
	v_sub_f32_e32 v24, v44, v24
	v_cvt_pk_bf16_f32 v2, v2, s0
	v_cvt_pk_bf16_f32 v26, v3, s0
	v_sub_f32_e32 v31, v41, v31
	v_sub_f32_e32 v30, v47, v30
	v_sub_f32_e32 v29, v40, v29
	v_sub_f32_e32 v28, v46, v28
	v_sub_f32_e32 v35, v43, v35
	v_sub_f32_e32 v34, v49, v34
	v_sub_f32_e32 v33, v42, v33
	v_sub_f32_e32 v32, v48, v32
	v_cvt_pk_bf16_f32 v3, v22, v23
	v_perm_b32 v2, v26, v2, s33
	v_cvt_pk_bf16_f32 v21, v21, v20
	v_cvt_pk_bf16_f32 v20, v24, v25
	v_add_u32_e32 v22, 0xd800, v120
	ds_write2_b64 v22, v[2:3], v[20:21] offset1:2
	v_cvt_pk_bf16_f32 v3, v30, v31
	v_cvt_pk_bf16_f32 v2, v28, v29
	v_cvt_pk_bf16_f32 v21, v34, v35
	v_cvt_pk_bf16_f32 v20, v32, v33
	ds_write2_b64 v22, v[2:3], v[20:21] offset0:4 offset1:6
	v_mov_b64_e32 v[34:35], v[18:19]
	v_mov_b64_e32 v[32:33], v[16:17]
	v_mov_b64_e32 v[30:31], v[14:15]
	v_mov_b64_e32 v[28:29], v[12:13]
	v_mov_b64_e32 v[26:27], v[10:11]
	v_mov_b64_e32 v[24:25], v[8:9]
	v_mov_b64_e32 v[22:23], v[6:7]
	v_mov_b64_e32 v[20:21], v[4:5]
	s_and_b64 vcc, exec, s[36:37]
	s_mov_b64 s[36:37], -1
	s_cbranch_vccz .LBB0_649

.LBB0_654:
	s_and_b32 s38, s50, 1
	s_mul_i32 s36, s38, 0x2400
	s_add_i32 s39, s36, 0
	s_add_i32 s39, s39, 0x1d400
	s_mov_b64 s[36:37], -1
	s_and_b64 vcc, exec, s[0:1]
	s_waitcnt lgkmcnt(0)
	s_barrier
	s_cbranch_vccz .LBB0_656
	v_add_u32_e32 v2, s39, v207
	ds_read_b128 v[36:39], v2
	ds_read_b128 v[40:43], v2 offset:32
	ds_read_b128 v[44:47], v1 offset:55296
	ds_read_b128 v[48:51], v1 offset:55328
	ds_read_b128 v[120:123], v2 offset:64
	ds_read_b128 v[208:211], v2 offset:96
	ds_read_b128 v[212:215], v1 offset:55360
	ds_read_b128 v[226:229], v1 offset:55392
	s_waitcnt lgkmcnt(5)
	v_mfma_f32_32x32x16_bf16 v[4:19], v[36:39], v[44:47], v[20:35]
	v_add_u32_e32 v1, s49, v132
	v_cndmask_b32_e64 v2, v203, v1, s[34:35]
	v_mov_b32_e32 v3, v0
	v_lshl_add_u64 v[2:3], s[58:59], 0, v[2:3]
	v_lshlrev_b64 v[2:3], 11, v[2:3]
	v_lshl_add_u64 v[2:3], v[118:119], 0, v[2:3]
	s_mov_b64 s[36:37], 0
	s_waitcnt lgkmcnt(4)
	v_mfma_f32_32x32x16_bf16 v[4:19], v[40:43], v[48:51], v[4:19]
	s_waitcnt lgkmcnt(1)
	v_mfma_f32_32x32x16_bf16 v[4:19], v[120:123], v[212:215], v[4:19]
	s_waitcnt lgkmcnt(0)
	v_mfma_f32_32x32x16_bf16 v[4:19], v[208:211], v[226:229], v[4:19]
	s_nop 11
	v_cvt_pk_bf16_f32 v37, v6, v7
	v_cvt_pk_bf16_f32 v36, v4, v5
	v_cvt_pk_bf16_f32 v39, v10, v11
	v_cvt_pk_bf16_f32 v38, v8, v9
	v_cvt_pk_bf16_f32 v41, v14, v15
	v_cvt_pk_bf16_f32 v40, v12, v13
	global_store_dwordx2 v[2:3], v[36:37], off
	global_store_dwordx2 v[2:3], v[38:39], off offset:16
	global_store_dwordx2 v[2:3], v[40:41], off offset:32
	v_cvt_pk_bf16_f32 v37, v18, v19
	v_cvt_pk_bf16_f32 v36, v16, v17
	global_store_dwordx2 v[2:3], v[36:37], off offset:48
.LBB0_656:
	s_andn2_b64 vcc, exec, s[36:37]
	s_cbranch_vccnz .LBB0_560
	v_add_u32_e32 v1, 0, v207
	v_add_u32_e32 v1, 0x16800, v1
	v_add_u32_e32 v18, s39, v206
	ds_read_b128 v[2:5], v1
	ds_read_b128 v[6:9], v1 offset:32
	ds_read_b128 v[10:13], v18
	ds_read_b128 v[14:17], v18 offset:32
	ds_read_b128 v[36:39], v1 offset:64
	ds_read_b128 v[40:43], v1 offset:96
	ds_read_b128 v[44:47], v18 offset:64
	ds_read_b128 v[48:51], v18 offset:96
	s_sub_i32 s36, 14, s38
	s_waitcnt lgkmcnt(5)
	v_mfma_f32_32x32x16_bf16 v[20:35], v[2:5], v[10:13], v[20:35]
	s_mulk_i32 s36, 0x2400
	s_add_i32 s36, s36, 0
	v_add_u32_e32 v1, s36, v205
	s_waitcnt lgkmcnt(4)
	v_mfma_f32_32x32x16_bf16 v[20:35], v[6:9], v[14:17], v[20:35]
	s_waitcnt lgkmcnt(1)
	v_mfma_f32_32x32x16_bf16 v[20:35], v[36:39], v[44:47], v[20:35]
	s_waitcnt lgkmcnt(0)
	v_mfma_f32_32x32x16_bf16 v[20:35], v[40:43], v[48:51], v[20:35]
	s_nop 11
	v_cvt_pk_bf16_f32 v3, v22, v23
	v_cvt_pk_bf16_f32 v2, v20, v21
	v_cvt_pk_bf16_f32 v5, v26, v27
	v_cvt_pk_bf16_f32 v4, v24, v25
	v_cvt_pk_bf16_f32 v7, v30, v31
	v_cvt_pk_bf16_f32 v6, v28, v29
	v_cvt_pk_bf16_f32 v9, v34, v35
	v_cvt_pk_bf16_f32 v8, v32, v33
	ds_write2_b64 v1, v[2:3], v[4:5] offset1:2
	ds_write2_b64 v1, v[6:7], v[8:9] offset0:4 offset1:6
	v_mov_b64_e32 v[4:5], v[20:21]
	v_mov_b64_e32 v[6:7], v[22:23]
	v_mov_b64_e32 v[8:9], v[24:25]
	v_mov_b64_e32 v[10:11], v[26:27]
	v_mov_b64_e32 v[12:13], v[28:29]
	v_mov_b64_e32 v[14:15], v[30:31]
	v_mov_b64_e32 v[16:17], v[32:33]
	v_mov_b64_e32 v[18:19], v[34:35]
	s_branch .LBB0_560
